# P57: SSD combine L2 touch-prefetch of rows 6..15 (4 arrays) right after the acquire
# baseline (speedup 1.0000x reference)
.LBB0_908:
	s_or_b64 exec, exec, s[2:3]
	s_waitcnt vmcnt(63) expcnt(7) lgkmcnt(15)
	s_barrier
	s_waitcnt lgkmcnt(0)
	s_load_dwordx4 s[8:11], s[18:19], 0x98
	v_lshlrev_b32_e32 v6, 2, v0
	s_and_b32 s35, s33, 15
	v_ashrrev_i32_e32 v8, 4, v0
	v_ashrrev_i32_e32 v7, 31, v6
	s_andn2_b64 vcc, exec, s[12:13]
	s_cbranch_vccnz .LBB0_934
	s_lshl_b32 s45, s34, 11
	s_lshl_b32 s2, s35, 7
	s_or_b32 s36, s45, s2
	s_add_i32 s2, s36, s61
	s_addk_i32 s36, 0x80
	v_add_u32_e32 v2, s0, v8
	v_ashrrev_i32_e32 v3, 31, v2
	s_waitcnt lgkmcnt(0)
	s_add_u32 s4, s10, s40
	v_lshl_add_u64 v[2:3], v[2:3], 2, s[8:9]
	s_addc_u32 s5, s11, s41
	global_load_dword v0, v[2:3], off
	v_lshl_add_u64 v[2:3], v[6:7], 2, s[4:5]
	v_readlane_b32 s4, v255, 9
	v_lshlrev_b64 v[10:11], 1, v[6:7]
	v_readlane_b32 s5, v255, 10
	s_ashr_i32 s3, s2, 31
	v_readlane_b32 s6, v255, 11
	v_lshl_add_u64 v[12:13], s[4:5], 0, v[10:11]
	v_readlane_b32 s4, v255, 20
	v_readlane_b32 s5, v255, 21
	v_readlane_b32 s7, v255, 12
	v_lshl_add_u64 v[16:17], s[14:15], 0, v[10:11]
	v_lshl_add_u64 v[14:15], s[4:5], 0, v[10:11]
	s_lshl_b64 s[4:5], s[2:3], 10
	v_lshl_add_u64 v[18:19], v[12:13], 0, s[4:5]
	s_mul_i32 s4, s2, 0x1600
	s_mul_hi_i32 s5, s2, 0x1600
	s_add_u32 s4, s6, s4
	s_addc_u32 s5, s7, s5
	v_lshl_add_u64 v[20:21], s[4:5], 0, v[10:11]
	s_lshl_b64 s[4:5], s[2:3], 9
	v_lshl_add_u64 v[22:23], v[14:15], 0, s[4:5]
	v_lshl_add_u64 v[24:25], v[16:17], 0, s[4:5]
	global_load_dwordx4 v[2:5], v[2:3], off
	s_nop 0
	global_load_dwordx2 v[18:19], v[18:19], off
	s_nop 0
	global_load_dwordx2 v[20:21], v[20:21], off offset:1024
	s_nop 0
	global_load_dwordx2 v[22:23], v[22:23], off
	s_nop 0
	global_load_dwordx2 v[24:25], v[24:25], off
	v_readlane_b32 s100, v255, 9
	v_readlane_b32 s101, v255, 10
	s_lshl_b64 s[98:99], s[2:3], 10
	s_add_u32 s100, s100, s98
	s_addc_u32 s101, s101, s99
	s_add_u32 s100, s100, 0xc000
	s_addc_u32 s101, s101, 0
	global_load_dwordx2 v[200:201], v10, s[100:101]
	s_add_u32 s100, s100, 0x2000
	s_addc_u32 s101, s101, 0
	global_load_dwordx2 v[200:201], v10, s[100:101]
	s_add_u32 s100, s100, 0x2000
	s_addc_u32 s101, s101, 0
	global_load_dwordx2 v[200:201], v10, s[100:101]
	s_add_u32 s100, s100, 0x2000
	s_addc_u32 s101, s101, 0
	global_load_dwordx2 v[200:201], v10, s[100:101]
	s_add_u32 s100, s100, 0x2000
	s_addc_u32 s101, s101, 0
	global_load_dwordx2 v[200:201], v10, s[100:101]
	s_add_u32 s100, s100, 0x2000
	s_addc_u32 s101, s101, 0
	global_load_dwordx2 v[200:201], v10, s[100:101]
	s_add_u32 s100, s100, 0x2000
	s_addc_u32 s101, s101, 0
	global_load_dwordx2 v[200:201], v10, s[100:101]
	s_add_u32 s100, s100, 0x2000
	s_addc_u32 s101, s101, 0
	global_load_dwordx2 v[200:201], v10, s[100:101]
	s_add_u32 s100, s100, 0x2000
	s_addc_u32 s101, s101, 0
	global_load_dwordx2 v[200:201], v10, s[100:101]
	s_add_u32 s100, s100, 0x2000
	s_addc_u32 s101, s101, 0
	global_load_dwordx2 v[200:201], v10, s[100:101]
	v_readlane_b32 s100, v255, 11
	v_readlane_b32 s101, v255, 12
	s_mul_i32 s98, s2, 0x1600
	s_mul_hi_i32 s99, s2, 0x1600
	s_add_u32 s100, s100, s98
	s_addc_u32 s101, s101, s99
	s_add_u32 s100, s100, 0x42000
	s_addc_u32 s101, s101, 0
	global_load_dwordx2 v[200:201], v10, s[100:101] offset:1024
	s_add_u32 s100, s100, 0xb000
	s_addc_u32 s101, s101, 0
	global_load_dwordx2 v[200:201], v10, s[100:101] offset:1024
	s_add_u32 s100, s100, 0xb000
	s_addc_u32 s101, s101, 0
	global_load_dwordx2 v[200:201], v10, s[100:101] offset:1024
	s_add_u32 s100, s100, 0xb000
	s_addc_u32 s101, s101, 0
	global_load_dwordx2 v[200:201], v10, s[100:101] offset:1024
	s_add_u32 s100, s100, 0xb000
	s_addc_u32 s101, s101, 0
	global_load_dwordx2 v[200:201], v10, s[100:101] offset:1024
	s_add_u32 s100, s100, 0xb000
	s_addc_u32 s101, s101, 0
	global_load_dwordx2 v[200:201], v10, s[100:101] offset:1024
	s_add_u32 s100, s100, 0xb000
	s_addc_u32 s101, s101, 0
	global_load_dwordx2 v[200:201], v10, s[100:101] offset:1024
	s_add_u32 s100, s100, 0xb000
	s_addc_u32 s101, s101, 0
	global_load_dwordx2 v[200:201], v10, s[100:101] offset:1024
	s_add_u32 s100, s100, 0xb000
	s_addc_u32 s101, s101, 0
	global_load_dwordx2 v[200:201], v10, s[100:101] offset:1024
	s_add_u32 s100, s100, 0xb000
	s_addc_u32 s101, s101, 0
	global_load_dwordx2 v[200:201], v10, s[100:101] offset:1024
	v_readlane_b32 s100, v255, 20
	v_readlane_b32 s101, v255, 21
	s_lshl_b64 s[98:99], s[2:3], 9
	s_add_u32 s100, s100, s98
	s_addc_u32 s101, s101, s99
	s_add_u32 s100, s100, 0x6000
	s_addc_u32 s101, s101, 0
	global_load_dwordx2 v[200:201], v10, s[100:101]
	s_add_u32 s100, s100, 0x1000
	s_addc_u32 s101, s101, 0
	global_load_dwordx2 v[200:201], v10, s[100:101]
	s_add_u32 s100, s100, 0x1000
	s_addc_u32 s101, s101, 0
	global_load_dwordx2 v[200:201], v10, s[100:101]
	s_add_u32 s100, s100, 0x1000
	s_addc_u32 s101, s101, 0
	global_load_dwordx2 v[200:201], v10, s[100:101]
	s_add_u32 s100, s100, 0x1000
	s_addc_u32 s101, s101, 0
	global_load_dwordx2 v[200:201], v10, s[100:101]
	s_add_u32 s100, s100, 0x1000
	s_addc_u32 s101, s101, 0
	global_load_dwordx2 v[200:201], v10, s[100:101]
	s_add_u32 s100, s100, 0x1000
	s_addc_u32 s101, s101, 0
	global_load_dwordx2 v[200:201], v10, s[100:101]
	s_add_u32 s100, s100, 0x1000
	s_addc_u32 s101, s101, 0
	global_load_dwordx2 v[200:201], v10, s[100:101]
	s_add_u32 s100, s100, 0x1000
	s_addc_u32 s101, s101, 0
	global_load_dwordx2 v[200:201], v10, s[100:101]
	s_add_u32 s100, s100, 0x1000
	s_addc_u32 s101, s101, 0
	global_load_dwordx2 v[200:201], v10, s[100:101]
	s_mov_b32 s100, s14
	s_mov_b32 s101, s15
	s_lshl_b64 s[98:99], s[2:3], 9
	s_add_u32 s100, s100, s98
	s_addc_u32 s101, s101, s99
	s_add_u32 s100, s100, 0x6000
	s_addc_u32 s101, s101, 0
	global_load_dwordx2 v[200:201], v10, s[100:101]
	s_add_u32 s100, s100, 0x1000
	s_addc_u32 s101, s101, 0
	global_load_dwordx2 v[200:201], v10, s[100:101]
	s_add_u32 s100, s100, 0x1000
	s_addc_u32 s101, s101, 0
	global_load_dwordx2 v[200:201], v10, s[100:101]
	s_add_u32 s100, s100, 0x1000
	s_addc_u32 s101, s101, 0
	global_load_dwordx2 v[200:201], v10, s[100:101]
	s_add_u32 s100, s100, 0x1000
	s_addc_u32 s101, s101, 0
	global_load_dwordx2 v[200:201], v10, s[100:101]
	s_add_u32 s100, s100, 0x1000
	s_addc_u32 s101, s101, 0
	global_load_dwordx2 v[200:201], v10, s[100:101]
	s_add_u32 s100, s100, 0x1000
	s_addc_u32 s101, s101, 0
	global_load_dwordx2 v[200:201], v10, s[100:101]
	s_add_u32 s100, s100, 0x1000
	s_addc_u32 s101, s101, 0
	global_load_dwordx2 v[200:201], v10, s[100:101]
	s_add_u32 s100, s100, 0x1000
	s_addc_u32 s101, s101, 0
	global_load_dwordx2 v[200:201], v10, s[100:101]
	s_add_u32 s100, s100, 0x1000
	s_addc_u32 s101, s101, 0
	global_load_dwordx2 v[200:201], v10, s[100:101]
	s_add_i32 s4, s2, 8
	s_cmp_ge_i32 s4, s36
	s_cbranch_scc1 .LBB0_911
	s_ashr_i32 s5, s4, 31
	s_lshl_b64 s[6:7], s[4:5], 10
	v_lshl_add_u64 v[26:27], v[12:13], 0, s[6:7]
	s_mul_i32 s6, s4, 0x1600
	v_readlane_b32 s42, v255, 11
	s_mul_hi_i32 s3, s4, 0x1600
	v_readlane_b32 s43, v255, 12
	s_add_u32 s6, s42, s6
	s_addc_u32 s7, s43, s3
	s_lshl_b64 s[4:5], s[4:5], 9
	v_lshl_add_u64 v[28:29], v[6:7], 1, s[6:7]
	v_lshl_add_u64 v[30:31], v[14:15], 0, s[4:5]
	v_lshl_add_u64 v[32:33], v[16:17], 0, s[4:5]
	global_load_dwordx2 v[26:27], v[26:27], off
	s_nop 0
	global_load_dwordx2 v[28:29], v[28:29], off offset:1024
	s_nop 0
	global_load_dwordx2 v[30:31], v[30:31], off
	s_nop 0
	global_load_dwordx2 v[32:33], v[32:33], off
